# mLSTM output section: rows r+1..r+3 of a lane's column take row r's address + k*0x2c00 instead of recomputing the 64-bit address chain (30 -> 6 instructions per chunk)
# speedup vs baseline: 1.0173x; 1.0173x over previous
; #define LAS __attribute__((address_space(3)))
; __device__ __forceinline__ unsigned cvt_pk_bf16(float lo, float hi) { f32x2_t v = {lo, hi}; bf16x2_t b = __builtin_convertvector(v, bf16x2_t); return __builtin_bit_cast(unsigned, b); }
; #define MFMA16(a, b, c) __builtin_amdgcn_mfma_f32_16x16x32_bf16((a), (b), (c), 0, 0, 0)
; __device__ __forceinline__ void mlstm_unit(KArg P, int L, int b, int h, int vs, LAS unsigned char* lds) {
;     ...
;             const LAS unsigned char* qp = lds + ML_QS + (ttile * 16 + c) * 528 + g * 16;
;             const LAS unsigned char* k0p = lds + ML_KS + ((par * 2 + 0) * 16 + c) * 528 + g * 16;
;             const LAS unsigned char* k1p = lds + ML_KS + ((par * 2 + 1) * 16 + c) * 528 + g * 16;
;             const LAS unsigned char* cp = lds + ML_CB + (par * 16 + c) * 528 + g * 16;
; #pragma unroll 2
;             for (int kk = 0; kk < 8; ++kk) {
;                 const bf16x8 a = *(const LAS bf16x8*)(qp + kk * 64);
;                 const bf16x8 b0 = *(const LAS bf16x8*)(k0p + kk * 64), b1 = *(const LAS bf16x8*)(k1p + kk * 64), bc = *(const LAS bf16x8*)(cp + kk * 64);
;                 accS0 = MFMA16(a, b0, accS0); accS1 = MFMA16(a, b1, accS1); accI = MFMA16(a, bc, accI);
;                 { const bf16x8 bn = *(const LAS bf16x8*)(lds + ML_NB + kk * 64 + g * 16); accN = MFMA16(a, bn, accN); } }
; #pragma unroll
;             for (int r = 0; r < 4; ++r) { const int t = ttile * 16 + 4 * g + r; const float Mt = GB[FL_MX + t];
;                 const int s0 = (par * 2) * 16 + c, s1 = s0 + 16;
;                 const float w0 = (s0 <= t) ? __expf(GB[FL_A + s0] - Mt) : 0.f, w1 = (s1 <= t) ? __expf(GB[FL_A + s1] - Mt) : 0.f;
;                 *(LAS bf16*)(lds + ML_PS + t * 144 + s0 * 2) = (bf16)(cvt_pk_bf16(accS0[r] * w0, 0.f) & 0xffffu);
;                 *(LAS bf16*)(lds + ML_PS + t * 144 + s1 * 2) = (bf16)(cvt_pk_bf16(accS1[r] * w1, 0.f) & 0xffffu); }
;         }
;         __syncthreads();
.LBB0_528:
	v_add_u32_e32 v240, 0x1bc00, v122
	v_add_u32_e32 v241, 0x22e40, v121
	ds_read_b128 v[180:183], v123
	ds_read_b128 v[184:187], v120
	ds_read_b128 v[188:191], v120 offset:8448
	ds_read_b128 v[192:195], v240
	ds_read_b128 v[196:199], v241
	ds_read_b128 v[200:203], v123 offset:64
	ds_read_b128 v[204:207], v120 offset:64
	ds_read_b128 v[208:211], v120 offset:8512
	ds_read_b128 v[212:215], v240 offset:64
	ds_read_b128 v[216:219], v241 offset:64
	ds_read_b128 v[220:223], v123 offset:128
	ds_read_b128 v[224:227], v120 offset:128
	ds_read_b128 v[228:231], v120 offset:8576
	ds_read_b128 v[232:235], v240 offset:128
	ds_read_b128 v[236:239], v241 offset:128
	s_waitcnt lgkmcnt(10)
	v_mfma_f32_16x16x32_bf16 v[72:75], v[180:183], v[184:187], 0
	v_mfma_f32_16x16x32_bf16 v[76:79], v[180:183], v[188:191], 0
	v_mfma_f32_16x16x32_bf16 v[64:67], v[180:183], v[192:195], 0
	v_mfma_f32_16x16x32_bf16 v[68:71], v[180:183], v[196:199], 0
	ds_read_b128 v[180:183], v123 offset:192
	ds_read_b128 v[184:187], v120 offset:192
	ds_read_b128 v[188:191], v120 offset:8640
	ds_read_b128 v[192:195], v240 offset:192
	ds_read_b128 v[196:199], v241 offset:192
	s_waitcnt lgkmcnt(10)
	v_mfma_f32_16x16x32_bf16 v[72:75], v[200:203], v[204:207], v[72:75]
	v_mfma_f32_16x16x32_bf16 v[76:79], v[200:203], v[208:211], v[76:79]
	v_mfma_f32_16x16x32_bf16 v[64:67], v[200:203], v[212:215], v[64:67]
	v_mfma_f32_16x16x32_bf16 v[68:71], v[200:203], v[216:219], v[68:71]
	ds_read_b128 v[200:203], v123 offset:256
	ds_read_b128 v[204:207], v120 offset:256
	ds_read_b128 v[208:211], v120 offset:8704
	ds_read_b128 v[212:215], v240 offset:256
	ds_read_b128 v[216:219], v241 offset:256
	s_waitcnt lgkmcnt(10)
	v_mfma_f32_16x16x32_bf16 v[72:75], v[220:223], v[224:227], v[72:75]
	v_mfma_f32_16x16x32_bf16 v[76:79], v[220:223], v[228:231], v[76:79]
	v_mfma_f32_16x16x32_bf16 v[64:67], v[220:223], v[232:235], v[64:67]
	v_mfma_f32_16x16x32_bf16 v[68:71], v[220:223], v[236:239], v[68:71]
	ds_read_b128 v[220:223], v123 offset:320
	ds_read_b128 v[224:227], v120 offset:320
	ds_read_b128 v[228:231], v120 offset:8768
	ds_read_b128 v[232:235], v240 offset:320
	ds_read_b128 v[236:239], v241 offset:320
	s_waitcnt lgkmcnt(10)
	v_mfma_f32_16x16x32_bf16 v[72:75], v[180:183], v[184:187], v[72:75]
	v_mfma_f32_16x16x32_bf16 v[76:79], v[180:183], v[188:191], v[76:79]
	v_mfma_f32_16x16x32_bf16 v[64:67], v[180:183], v[192:195], v[64:67]
	v_mfma_f32_16x16x32_bf16 v[68:71], v[180:183], v[196:199], v[68:71]
	ds_read_b128 v[180:183], v123 offset:384
	ds_read_b128 v[184:187], v120 offset:384
	ds_read_b128 v[188:191], v120 offset:8832
	ds_read_b128 v[192:195], v240 offset:384
	ds_read_b128 v[196:199], v241 offset:384
	s_waitcnt lgkmcnt(10)
	v_mfma_f32_16x16x32_bf16 v[72:75], v[200:203], v[204:207], v[72:75]
	v_mfma_f32_16x16x32_bf16 v[76:79], v[200:203], v[208:211], v[76:79]
	v_mfma_f32_16x16x32_bf16 v[64:67], v[200:203], v[212:215], v[64:67]
	v_mfma_f32_16x16x32_bf16 v[68:71], v[200:203], v[216:219], v[68:71]
	ds_read_b128 v[200:203], v123 offset:448
	ds_read_b128 v[204:207], v120 offset:448
	ds_read_b128 v[208:211], v120 offset:8896
	ds_read_b128 v[212:215], v240 offset:448
	ds_read_b128 v[216:219], v241 offset:448
	s_waitcnt lgkmcnt(10)
	v_mfma_f32_16x16x32_bf16 v[72:75], v[220:223], v[224:227], v[72:75]
	v_mfma_f32_16x16x32_bf16 v[76:79], v[220:223], v[228:231], v[76:79]
	v_mfma_f32_16x16x32_bf16 v[64:67], v[220:223], v[232:235], v[64:67]
	v_mfma_f32_16x16x32_bf16 v[68:71], v[220:223], v[236:239], v[68:71]
	s_waitcnt lgkmcnt(5)
	v_mfma_f32_16x16x32_bf16 v[72:75], v[180:183], v[184:187], v[72:75]
	v_mfma_f32_16x16x32_bf16 v[76:79], v[180:183], v[188:191], v[76:79]
	v_mfma_f32_16x16x32_bf16 v[64:67], v[180:183], v[192:195], v[64:67]
	v_mfma_f32_16x16x32_bf16 v[68:71], v[180:183], v[196:199], v[68:71]
	s_waitcnt lgkmcnt(0)
	v_mfma_f32_16x16x32_bf16 v[72:75], v[200:203], v[204:207], v[72:75]
	v_mfma_f32_16x16x32_bf16 v[76:79], v[200:203], v[208:211], v[76:79]
	v_mfma_f32_16x16x32_bf16 v[64:67], v[200:203], v[212:215], v[64:67]
	v_mfma_f32_16x16x32_bf16 v[68:71], v[200:203], v[216:219], v[68:71]
	s_bitcmp1_b32 s43, 0
	s_cselect_b32 s4, 0x5a0, 0
	s_add_i32 s48, s4, 0
	s_add_i32 s48, s48, 0x22200
	v_lshl_add_u32 v141, v86, 2, s48
	v_lshl_add_u32 v142, v108, 2, s48
	ds_read_b128 v[180:183], v141 offset:256
	ds_read_b32 v184, v142
	ds_read_b32 v185, v142 offset:64
	v_add_u32_e32 v202, v114, v109
	v_add_u32_e32 v203, v114, v110
	v_add_u32_e32 v204, v115, v109
	v_add_u32_e32 v205, v115, v110
	v_add_u32_e32 v206, v116, v109
	v_add_u32_e32 v207, v116, v110
	v_add_u32_e32 v208, v117, v109
	v_add_u32_e32 v209, v117, v110
	s_waitcnt lgkmcnt(0)
	v_sub_f32_e32 v186, v184, v180
	v_sub_f32_e32 v187, v185, v180
	v_sub_f32_e32 v188, v184, v181
	v_sub_f32_e32 v189, v185, v181
	v_sub_f32_e32 v190, v184, v182
	v_sub_f32_e32 v191, v185, v182
	v_sub_f32_e32 v192, v184, v183
	v_sub_f32_e32 v193, v185, v183
	v_mul_f32_e32 v186, 0x3fb8aa3b, v186
	v_mul_f32_e32 v187, 0x3fb8aa3b, v187
	v_mul_f32_e32 v188, 0x3fb8aa3b, v188
	v_mul_f32_e32 v189, 0x3fb8aa3b, v189
	v_mul_f32_e32 v190, 0x3fb8aa3b, v190
	v_mul_f32_e32 v191, 0x3fb8aa3b, v191
	v_mul_f32_e32 v192, 0x3fb8aa3b, v192
	v_mul_f32_e32 v193, 0x3fb8aa3b, v193
	v_exp_f32_e32 v186, v186
	v_exp_f32_e32 v187, v187
	v_exp_f32_e32 v188, v188
	v_exp_f32_e32 v189, v189
	v_exp_f32_e32 v190, v190
	v_exp_f32_e32 v191, v191
	v_exp_f32_e32 v192, v192
	v_exp_f32_e32 v193, v193
	v_cndmask_b32_e64 v186, 0, v186, s[16:17]
	v_cndmask_b32_e64 v187, 0, v187, s[18:19]
	v_cndmask_b32_e64 v188, 0, v188, s[20:21]
	v_cndmask_b32_e64 v189, 0, v189, s[22:23]
	v_cndmask_b32_e64 v190, 0, v190, s[24:25]
	v_cndmask_b32_e64 v191, 0, v191, s[26:27]
	v_cndmask_b32_e64 v192, 0, v192, s[28:29]
	v_cndmask_b32_e64 v193, 0, v193, s[30:31]
	v_mul_f32_e32 v186, v72, v186
	v_mul_f32_e32 v187, v76, v187
	v_mul_f32_e32 v188, v73, v188
	v_mul_f32_e32 v189, v77, v189
	v_mul_f32_e32 v190, v74, v190
	v_mul_f32_e32 v191, v78, v191
	v_mul_f32_e32 v192, v75, v192
	v_mul_f32_e32 v193, v79, v193
	v_cvt_pk_bf16_f32 v186, v186, s0
	v_cvt_pk_bf16_f32 v187, v187, s0
	v_cvt_pk_bf16_f32 v188, v188, s0
	v_cvt_pk_bf16_f32 v189, v189, s0
	v_cvt_pk_bf16_f32 v190, v190, s0
	v_cvt_pk_bf16_f32 v191, v191, s0
	v_cvt_pk_bf16_f32 v192, v192, s0
	v_cvt_pk_bf16_f32 v193, v193, s0
	ds_write_b16 v202, v186
	ds_write_b16 v203, v187
	ds_write_b16 v204, v188
	ds_write_b16 v205, v189
	ds_write_b16 v206, v190
	ds_write_b16 v207, v191
	ds_write_b16 v208, v192
	ds_write_b16 v209, v193
	v_add_u32_e32 v226, s48, v107
	v_mov_b32_e32 v227, s48
	s_waitcnt lgkmcnt(0)
	s_barrier
; __device__ __forceinline__ void mlstm_unit(KArg P, int L, int b, int h, int vs, LAS unsigned char* lds) {
;     ...
;             f32x4 accP = (f32x4){0.f, 0.f, 0.f, 0.f}, accR = accP;
;             const bf16x8 ones8 = (bf16x8){0x3f80, 0x3f80, 0x3f80, 0x3f80, 0x3f80, 0x3f80, 0x3f80, 0x3f80};
; #pragma unroll
;             for (int ks = 0; ks < 2; ++ks) {
;                 const bf16x8 a = *(const LAS bf16x8*)(lds + ML_PS + (ttile * 16 + c) * 144 + ks * 64 + g * 16);
;                 const bf16x8 bv = *(const LAS bf16x8*)(lds + ML_VT + (par * 16 + c) * 144 + ks * 64 + g * 16);
;                 accP = MFMA16(a, bv, accP); accR = MFMA16(a, ones8, accR); }
; #pragma unroll
;             for (int r = 0; r < 4; ++r) { const int t = ttile * 16 + 4 * g + r; const float wi = GB[FL_WIN + t];
;                 const float num = accP[r] + wi * accI[r]; const float den = accR[r] + wi * accN[r];
;                 const float hv = num * __builtin_amdgcn_rcpf(fmaxf(fabsf(den), GB[FL_FLOOR + t]));
;                 Z[(rowbase + t0 + t) * ZW + ZC_V + h * 256 + vs * 32 + par * 16 + c] = (bf16)(cvt_pk_bf16(hv, 0.f) & 0xffffu); }
;             const float decay = GB[FL_SC];
;             const LAS unsigned char* wsb = (const LAS unsigned char*)(GB + FL_WSTB);
; #pragma unroll
;             for (int kt = 0; kt < 2; ++kt) {
;                 bf16x8 bk[2];
; #pragma unroll
;                 for (int ks = 0; ks < 2; ++ks) bk[ks] = *(const LAS bf16x8*)(lds + ML_KT + ((2 * w + kt) * 16 + c) * 144 + (((ks * 4 + g) ^ ((2 * w + kt) & 7)) * 16));
; #pragma unroll
;                 for (int vt = 0; vt < 2; ++vt) {
;                     f32x4 cc = Cacc[kt][vt] * decay;
; #pragma unroll
;                     for (int ks = 0; ks < 2; ++ks) { const bf16x8 a = *(const LAS bf16x8*)(lds + ML_VWT + (vt * 16 + c) * 144 + ks * 64 + g * 16); cc = MFMA16(a, bk[ks], cc); }
;                     Cacc[kt][vt] = cc;
; #pragma unroll
;                     for (int r = 0; r < 4; ++r) *(LAS bf16*)(lds + ML_CB + (vt * 16 + 4 * g + r) * 528 + ((2 * w + kt) * 16 + c) * 2) = (bf16)(cvt_pk_bf16(cc[r], 0.f) & 0xffffu);
;                 }
;                 f32x4 cn = Cn[kt] * decay;
; #pragma unroll
;                 for (int ks = 0; ks < 2; ++ks) { const bf16x8 an = *(const LAS bf16x8*)(wsb + ks * 64 + g * 16); cn = MFMA16(an, bk[ks], cn); }
;                 Cn[kt] = cn;
	ds_read_b128 v[72:75], v124
	ds_read_b128 v[76:79], v125
	v_readlane_b32 s72, v254, 30
	v_readlane_b32 s74, v254, 32
	v_readlane_b32 s75, v254, 33
	v_readlane_b32 s73, v254, 31
	ds_read_b128 v[146:149], v124 offset:64
	ds_read_b128 v[150:153], v125 offset:64
	ds_read_b128 v[180:183], v126
	ds_read_b128 v[184:187], v127
	ds_read_b128 v[196:199], v140
	ds_read_b128 v[200:203], v140 offset:64
	ds_read_b128 v[204:207], v140 offset:2304
	ds_read_b128 v[208:211], v140 offset:2368
	ds_read_b128 v[212:215], v226 offset:1312
	ds_read_b128 v[216:219], v226 offset:1376
	ds_read_b128 v[188:191], v129
	ds_read_b128 v[192:195], v130
	ds_read_b32 v224, v227 offset:1280
	v_mov_b64_e32 v[144:145], s[74:75]
	v_mov_b64_e32 v[142:143], s[72:73]
	s_waitcnt lgkmcnt(13)
	v_mfma_f32_16x16x32_bf16 v[76:79], v[72:75], v[76:79], 0
	s_lshl_b32 s4, s43, 6
	s_add_u32 s46, s2, s4
	v_readlane_b32 s4, v254, 43
	v_mfma_f32_16x16x32_bf16 v[72:75], v[72:75], v[142:145], 0
	s_addc_u32 s47, s3, 0
	v_readlane_b32 s5, v254, 44
	s_movk_i32 s49, 0x1000
	s_waitcnt lgkmcnt(11)
	v_mfma_f32_16x16x32_bf16 v[76:79], v[146:149], v[150:153], v[76:79]
	v_lshl_add_u64 v[150:151], s[46:47], 0, v[86:87]
	v_mov_b64_e32 v[152:153], s[4:5]
	v_mad_u64_u32 v[156:157], s[66:67], v150, s68, v[152:153]
	v_mfma_f32_16x16x32_bf16 v[72:75], v[146:149], v[142:145], v[72:75]
	ds_read_b128 v[142:145], v141 offset:512
	ds_read_b128 v[146:149], v141 offset:768
	v_readlane_b32 s4, v254, 34
	v_mad_i32_i24 v157, v151, s68, v157
	v_readlane_b32 s5, v254, 35
	s_waitcnt lgkmcnt(1)
	s_nop 1
	v_fma_f32 v68, v68, v142, v72
	s_waitcnt lgkmcnt(0)
	v_max_f32_e32 v72, v146, v146
	v_max_f32_e64 v68, |v68|, v72
	s_lshl_b32 s4, s52, 1
	v_rcp_f32_e32 v68, v68
	v_lshl_add_u64 v[150:151], v[156:157], 0, s[4:5]
	s_mov_b32 s41, s5
	v_lshl_add_u64 v[150:151], v[150:151], 0, s[40:41]
	s_mov_b32 s43, s5
	v_lshl_add_u64 v[150:151], v[150:151], 0, s[42:43]
	v_fma_f32 v64, v64, v142, v76
	v_lshl_add_u64 v[150:151], v[150:151], 0, v[0:1]
	v_mul_f32_e32 v64, v64, v68
	v_add_co_u32_e32 v150, vcc, s49, v150
	v_cvt_pk_bf16_f32 v64, v64, s0
	s_nop 0
	v_addc_co_u32_e32 v151, vcc, 0, v151, vcc
	global_store_short v[150:151], v64, off
	v_fma_f32 v64, v65, v143, v77
	v_fma_f32 v65, v69, v143, v73
	v_max_f32_e32 v68, v147, v147
	v_max_f32_e64 v65, |v65|, v68
	v_rcp_f32_e32 v65, v65
	v_fmac_f32_e32 v75, v71, v145
	v_fmac_f32_e32 v79, v67, v145
	v_mul_f32_e32 v64, v64, v65
	v_cvt_pk_bf16_f32 v72, v64, s0
	s_mov_b64 s[66:67], 0x2c00
	v_lshl_add_u64 v[64:65], v[150:151], 0, s[66:67]
	global_store_short v[64:65], v72, off
	v_fma_f32 v64, v66, v144, v78
	v_fma_f32 v65, v70, v144, v74
	v_max_f32_e32 v66, v148, v148
	v_max_f32_e64 v65, |v65|, v66
	v_rcp_f32_e32 v65, v65
	v_add_u32_e32 v70, s48, v107
	v_mul_f32_e32 v64, v64, v65
	v_cvt_pk_bf16_f32 v66, v64, s0
	s_mov_b64 s[66:67], 0x5800
	v_lshl_add_u64 v[64:65], v[150:151], 0, s[66:67]
	global_store_short v[64:65], v66, off
	v_max_f32_e32 v64, v149, v149
	v_max_f32_e64 v64, |v75|, v64
	v_rcp_f32_e32 v64, v64
	s_nop 0
	v_mul_f32_e32 v64, v79, v64
	v_cvt_pk_bf16_f32 v68, v64, s0
	s_mov_b64 s[66:67], 0x8400
	v_lshl_add_u64 v[64:65], v[150:151], 0, s[66:67]
	s_mov_b32 s47, s5
	global_store_short v[64:65], v68, off
	v_writelane_b32 v254, s46, 34
	v_writelane_b32 v254, s47, 35
	v_pk_mul_f32 v[62:63], v[62:63], v[224:225] op_sel_hi:[1,0]
	v_pk_mul_f32 v[60:61], v[60:61], v[224:225] op_sel_hi:[1,0]
	v_pk_mul_f32 v[50:51], v[50:51], v[224:225] op_sel_hi:[1,0]
	v_pk_mul_f32 v[48:49], v[48:49], v[224:225] op_sel_hi:[1,0]
	v_pk_mul_f32 v[58:59], v[58:59], v[224:225] op_sel_hi:[1,0]
	v_pk_mul_f32 v[56:57], v[56:57], v[224:225] op_sel_hi:[1,0]
	v_pk_mul_f32 v[54:55], v[54:55], v[224:225] op_sel_hi:[1,0]
	v_pk_mul_f32 v[52:53], v[52:53], v[224:225] op_sel_hi:[1,0]
	v_pk_mul_f32 v[42:43], v[42:43], v[224:225] op_sel_hi:[1,0]
	v_pk_mul_f32 v[40:41], v[40:41], v[224:225] op_sel_hi:[1,0]
	v_pk_mul_f32 v[46:47], v[46:47], v[224:225] op_sel_hi:[1,0]
	v_pk_mul_f32 v[44:45], v[44:45], v[224:225] op_sel_hi:[1,0]
	v_mfma_f32_16x16x32_bf16 v[60:63], v[196:199], v[180:183], v[60:63]
	v_mfma_f32_16x16x32_bf16 v[60:63], v[200:203], v[184:187], v[60:63]
	v_mfma_f32_16x16x32_bf16 v[48:51], v[204:207], v[180:183], v[48:51]
	v_mfma_f32_16x16x32_bf16 v[48:51], v[208:211], v[184:187], v[48:51]
	v_mfma_f32_16x16x32_bf16 v[56:59], v[212:215], v[180:183], v[56:59]
	v_mfma_f32_16x16x32_bf16 v[56:59], v[216:219], v[184:187], v[56:59]
	v_mfma_f32_16x16x32_bf16 v[52:55], v[196:199], v[188:191], v[52:55]
	v_mfma_f32_16x16x32_bf16 v[52:55], v[200:203], v[192:195], v[52:55]
	v_mfma_f32_16x16x32_bf16 v[40:43], v[204:207], v[188:191], v[40:43]
	v_mfma_f32_16x16x32_bf16 v[40:43], v[208:211], v[192:195], v[40:43]
	v_mfma_f32_16x16x32_bf16 v[44:47], v[212:215], v[188:191], v[44:47]
	v_mfma_f32_16x16x32_bf16 v[44:47], v[216:219], v[192:195], v[44:47]
	v_cvt_pk_bf16_f32 v228, v60, s0
	ds_write_b16 v128, v228
	v_cvt_pk_bf16_f32 v229, v61, s0
	ds_write_b16 v128, v229 offset:528
	v_cvt_pk_bf16_f32 v230, v62, s0
	ds_write_b16 v128, v230 offset:1056
	v_cvt_pk_bf16_f32 v231, v63, s0
	ds_write_b16 v128, v231 offset:1584
	v_cvt_pk_bf16_f32 v228, v48, s0
	ds_write_b16 v128, v228 offset:8448
	v_cvt_pk_bf16_f32 v229, v49, s0
	ds_write_b16 v128, v229 offset:8976
	v_cvt_pk_bf16_f32 v230, v50, s0
	ds_write_b16 v128, v230 offset:9504
	v_cvt_pk_bf16_f32 v231, v51, s0
	ds_write_b16 v128, v231 offset:10032
	s_and_saveexec_b64 s[46:47], s[12:13]
	v_cvt_pk_bf16_f32 v64, v56, v57
	v_add_u32_e32 v65, s63, v118
	ds_write_b16 v65, v64
	s_or_b64 exec, exec, s[46:47]
	v_cvt_pk_bf16_f32 v228, v52, s0
	ds_write_b16 v131, v228
	v_cvt_pk_bf16_f32 v229, v53, s0
	ds_write_b16 v131, v229 offset:528
	v_cvt_pk_bf16_f32 v230, v54, s0
	ds_write_b16 v131, v230 offset:1056
	v_cvt_pk_bf16_f32 v231, v55, s0
	ds_write_b16 v131, v231 offset:1584
	v_cvt_pk_bf16_f32 v228, v40, s0
	ds_write_b16 v131, v228 offset:8448
	v_cvt_pk_bf16_f32 v229, v41, s0
	ds_write_b16 v131, v229 offset:8976
	v_cvt_pk_bf16_f32 v230, v42, s0
	ds_write_b16 v131, v230 offset:9504
	v_cvt_pk_bf16_f32 v231, v43, s0
	ds_write_b16 v131, v231 offset:10032
	s_and_saveexec_b64 s[46:47], s[12:13]
	s_cbranch_execnz .LBB0_557
	s_or_b64 exec, exec, s[46:47]
	s_or_b64 s[34:35], s[36:37], s[34:35]
	s_and_b64 vcc, exec, s[34:35]
	s_cbranch_vccz .LBB0_558
